# sgu unit MFMA part: weight fragments of the next output group prefetched during the previous group's epilogue; u/bias loads issued at group start instead of after the MFMAs
# baseline (speedup 1.0000x reference)
.LBB0_286:
	global_load_dwordx4 v[212:215], v[30:31], off offset:-64
	global_load_dwordx4 v[216:219], v[30:31], off
	global_load_dword v8, v[0:1], off
	s_mov_b32 s24, 0
	v_mov_b64_e32 v[4:5], v[28:29]
	v_mov_b32_e32 v9, v55

.LBB0_289:
	s_waitcnt vmcnt(0)
	v_mov_b32_e32 v26, v220
	v_mov_b32_e32 v27, v221
	v_mov_b32_e32 v20, v228
	v_mov_b32_e32 v110, v222
	v_mov_b32_e32 v111, v223
	v_mov_b32_e32 v112, v224
	v_mov_b32_e32 v113, v225
	v_mov_b32_e32 v114, v226
	v_mov_b32_e32 v115, v227
	v_mov_b32_e32 v132, v16
	v_lshl_add_u64 v[22:23], v[42:43], 0, s[2:3]
	s_mov_b64 s[8:9], 0x8000
	s_add_u32 s2, s2, 0x80
	v_lshl_add_u64 v[48:49], v[48:49], 0, s[8:9]
	s_mov_b64 s[8:9], 0x200
	global_load_dwordx4 v[212:215], v[48:49], off offset:-64
	global_load_dwordx4 v[216:219], v[48:49], off
	s_addc_u32 s3, s3, 0
	v_lshl_add_u64 v[46:47], v[46:47], 0, s[8:9]
	v_add_u32_e32 v37, 0x4200, v37
	s_cmpk_lg_i32 s2, 0x200
	v_lshlrev_b32_e32 v57, 16, v26
	v_mul_f32_e32 v21, 0x3d372713, v57
	v_mul_f32_e32 v21, v21, v57
	v_fma_f32 v21, v21, v57, v57
	v_mul_f32_e32 v21, 0x3f4c422a, v21
	v_add_f32_e32 v21, v21, v21
	v_mul_f32_e32 v21, 0x3fb8aa3b, v21
	v_exp_f32_e32 v21, v21
	v_mul_f32_e32 v57, 0.5, v57
	v_add_f32_e32 v21, 1.0, v21
	v_rcp_f32_e32 v21, v21
	s_nop 0
	v_fma_f32 v21, v21, -2.0, 1.0
	v_pk_add_f32 v[58:59], v[20:21], v[132:133]
	v_mov_b32_e32 v132, v17
	v_mul_f32_e32 v16, v57, v59
	v_mul_f32_e32 v57, v58, v16
	v_and_b32_e32 v16, 0xffff0000, v26
	v_mul_f32_e32 v21, 0x3d372713, v16
	v_mul_f32_e32 v21, v21, v16
	v_fma_f32 v21, v21, v16, v16
	v_mul_f32_e32 v21, 0x3f4c422a, v21
	v_add_f32_e32 v21, v21, v21
	v_mul_f32_e32 v21, 0x3fb8aa3b, v21
	v_exp_f32_e32 v21, v21
	v_mul_f32_e32 v26, 0.5, v16
	v_add_f32_e32 v21, 1.0, v21
	v_rcp_f32_e32 v21, v21
	s_nop 0
	v_fma_f32 v21, v21, -2.0, 1.0
	v_pk_add_f32 v[16:17], v[20:21], v[132:133]
	v_mov_b32_e32 v132, v18
	v_mul_f32_e32 v17, v26, v17
	v_mul_f32_e32 v16, v16, v17
	v_lshlrev_b32_e32 v17, 16, v27
	v_mul_f32_e32 v21, 0x3d372713, v17
	v_mul_f32_e32 v21, v21, v17
	v_fma_f32 v21, v21, v17, v17
	v_mul_f32_e32 v21, 0x3f4c422a, v21
	v_add_f32_e32 v21, v21, v21
	v_mul_f32_e32 v21, 0x3fb8aa3b, v21
	v_exp_f32_e32 v21, v21
	v_and_b32_e32 v18, 0xffff0000, v27
	v_mul_f32_e32 v17, 0.5, v17
	v_mul_f32_e32 v26, 0.5, v18
	v_add_f32_e32 v21, 1.0, v21
	v_rcp_f32_e32 v21, v21
	v_cvt_pk_bf16_f32 v16, v57, v16
	s_nop 0
	v_fma_f32 v21, v21, -2.0, 1.0
	v_pk_add_f32 v[58:59], v[20:21], v[132:133]
	v_mul_f32_e32 v21, 0x3d372713, v18
	v_mul_f32_e32 v21, v21, v18
	v_fma_f32 v21, v21, v18, v18
	v_mul_f32_e32 v21, 0x3f4c422a, v21
	v_add_f32_e32 v21, v21, v21
	v_mul_f32_e32 v21, 0x3fb8aa3b, v21
	v_exp_f32_e32 v21, v21
	v_mov_b32_e32 v132, v19
	v_mul_f32_e32 v17, v17, v59
	v_mul_f32_e32 v17, v58, v17
	v_add_f32_e32 v21, 1.0, v21
	v_rcp_f32_e32 v21, v21
	s_nop 0
	v_fma_f32 v21, v21, -2.0, 1.0
	v_pk_add_f32 v[18:19], v[20:21], v[132:133]
	v_mov_b32_e32 v132, v12
	v_mul_f32_e32 v19, v26, v19
	v_mul_f32_e32 v18, v18, v19
	v_cvt_pk_bf16_f32 v17, v17, v18
	global_store_dwordx2 v[22:23], v[16:17], off offset:1536
	v_mov_b32_e32 v16, v110
	v_mov_b32_e32 v17, v111
	v_lshlrev_b32_e32 v18, 16, v16
	v_mul_f32_e32 v19, 0x3d372713, v18
	v_mul_f32_e32 v19, v19, v18
	v_fma_f32 v19, v19, v18, v18
	v_mul_f32_e32 v19, 0x3f4c422a, v19
	v_add_f32_e32 v19, v19, v19
	v_mul_f32_e32 v19, 0x3fb8aa3b, v19
	v_exp_f32_e32 v19, v19
	v_mul_f32_e32 v26, 0.5, v18
	v_add_f32_e32 v19, 1.0, v19
	v_rcp_f32_e32 v19, v19
	s_nop 0
	v_fma_f32 v21, v19, -2.0, 1.0
	v_pk_add_f32 v[18:19], v[20:21], v[132:133]
	v_mov_b32_e32 v132, v13
	v_mul_f32_e32 v12, v26, v19
	v_mul_f32_e32 v18, v18, v12
	v_and_b32_e32 v12, 0xffff0000, v16
	v_mul_f32_e32 v16, 0x3d372713, v12
	v_mul_f32_e32 v16, v16, v12
	v_fma_f32 v16, v16, v12, v12
	v_mul_f32_e32 v16, 0x3f4c422a, v16
	v_add_f32_e32 v16, v16, v16
	v_mul_f32_e32 v16, 0x3fb8aa3b, v16
	v_exp_f32_e32 v16, v16
	s_nop 0
	v_add_f32_e32 v16, 1.0, v16
	v_rcp_f32_e32 v16, v16
	s_nop 0
	v_fma_f32 v21, v16, -2.0, 1.0
	v_mul_f32_e32 v16, 0.5, v12
	v_pk_add_f32 v[12:13], v[20:21], v[132:133]
	v_mov_b32_e32 v132, v14
	v_mul_f32_e32 v13, v16, v13
	v_mul_f32_e32 v12, v12, v13
	v_lshlrev_b32_e32 v13, 16, v17
	v_mul_f32_e32 v16, 0x3d372713, v13
	v_mul_f32_e32 v16, v16, v13
	v_fma_f32 v16, v16, v13, v13
	v_mul_f32_e32 v16, 0x3f4c422a, v16
	v_add_f32_e32 v16, v16, v16
	v_mul_f32_e32 v16, 0x3fb8aa3b, v16
	v_exp_f32_e32 v16, v16
	v_and_b32_e32 v14, 0xffff0000, v17
	v_cvt_pk_bf16_f32 v12, v18, v12
	v_mul_f32_e32 v13, 0.5, v13
	v_add_f32_e32 v16, 1.0, v16
	v_rcp_f32_e32 v16, v16
	s_nop 0
	v_fma_f32 v21, v16, -2.0, 1.0
	v_mul_f32_e32 v16, 0x3d372713, v14
	v_mul_f32_e32 v16, v16, v14
	v_fma_f32 v16, v16, v14, v14
	v_mul_f32_e32 v16, 0x3f4c422a, v16
	v_add_f32_e32 v16, v16, v16
	v_mul_f32_e32 v16, 0x3fb8aa3b, v16
	v_exp_f32_e32 v16, v16
	v_pk_add_f32 v[18:19], v[20:21], v[132:133]
	v_mov_b32_e32 v132, v15
	v_mul_f32_e32 v13, v13, v19
	v_add_f32_e32 v16, 1.0, v16
	v_rcp_f32_e32 v16, v16
	v_mul_f32_e32 v13, v18, v13
	v_fma_f32 v21, v16, -2.0, 1.0
	v_mul_f32_e32 v16, 0.5, v14
	v_pk_add_f32 v[14:15], v[20:21], v[132:133]
	v_mov_b32_e32 v132, v8
	v_mul_f32_e32 v15, v16, v15
	v_mul_f32_e32 v14, v14, v15
	v_cvt_pk_bf16_f32 v13, v13, v14
	global_store_dwordx2 v[22:23], v[12:13], off offset:1568
	v_mov_b32_e32 v12, v112
	v_mov_b32_e32 v13, v113
	v_lshlrev_b32_e32 v14, 16, v12
	v_mul_f32_e32 v15, 0x3d372713, v14
	v_mul_f32_e32 v15, v15, v14
	v_fma_f32 v15, v15, v14, v14
	v_mul_f32_e32 v15, 0x3f4c422a, v15
	v_add_f32_e32 v15, v15, v15
	v_mul_f32_e32 v15, 0x3fb8aa3b, v15
	v_exp_f32_e32 v15, v15
	v_mul_f32_e32 v16, 0.5, v14
	v_add_f32_e32 v15, 1.0, v15
	v_rcp_f32_e32 v15, v15
	s_nop 0
	v_fma_f32 v21, v15, -2.0, 1.0
	v_pk_add_f32 v[14:15], v[20:21], v[132:133]
	v_mov_b32_e32 v132, v9
	v_mul_f32_e32 v8, v16, v15
	v_mul_f32_e32 v14, v14, v8
	v_and_b32_e32 v8, 0xffff0000, v12
	v_mul_f32_e32 v12, 0x3d372713, v8
	v_mul_f32_e32 v12, v12, v8
	v_fma_f32 v12, v12, v8, v8
	v_mul_f32_e32 v12, 0x3f4c422a, v12
	v_add_f32_e32 v12, v12, v12
	v_mul_f32_e32 v12, 0x3fb8aa3b, v12
	v_exp_f32_e32 v12, v12
	s_nop 0
	v_add_f32_e32 v12, 1.0, v12
	v_rcp_f32_e32 v12, v12
	s_nop 0
	v_fma_f32 v21, v12, -2.0, 1.0
	v_mul_f32_e32 v12, 0.5, v8
	v_pk_add_f32 v[8:9], v[20:21], v[132:133]
	v_mov_b32_e32 v132, v10
	v_mul_f32_e32 v9, v12, v9
	v_mul_f32_e32 v8, v8, v9
	v_lshlrev_b32_e32 v9, 16, v13
	v_mul_f32_e32 v12, 0x3d372713, v9
	v_mul_f32_e32 v12, v12, v9
	v_fma_f32 v12, v12, v9, v9
	v_mul_f32_e32 v12, 0x3f4c422a, v12
	v_add_f32_e32 v12, v12, v12
	v_mul_f32_e32 v12, 0x3fb8aa3b, v12
	v_exp_f32_e32 v12, v12
	v_and_b32_e32 v10, 0xffff0000, v13
	v_cvt_pk_bf16_f32 v8, v14, v8
	v_mul_f32_e32 v9, 0.5, v9
	v_add_f32_e32 v12, 1.0, v12
	v_rcp_f32_e32 v12, v12
	s_nop 0
	v_fma_f32 v21, v12, -2.0, 1.0
	v_mul_f32_e32 v12, 0x3d372713, v10
	v_mul_f32_e32 v12, v12, v10
	v_fma_f32 v12, v12, v10, v10
	v_mul_f32_e32 v12, 0x3f4c422a, v12
	v_add_f32_e32 v12, v12, v12
	v_mul_f32_e32 v12, 0x3fb8aa3b, v12
	v_exp_f32_e32 v12, v12
	v_pk_add_f32 v[14:15], v[20:21], v[132:133]
	v_mov_b32_e32 v132, v11
	v_mul_f32_e32 v9, v9, v15
	v_add_f32_e32 v12, 1.0, v12
	v_rcp_f32_e32 v12, v12
	v_mul_f32_e32 v9, v14, v9
	v_fma_f32 v21, v12, -2.0, 1.0
	v_mul_f32_e32 v12, 0.5, v10
	v_pk_add_f32 v[10:11], v[20:21], v[132:133]
	v_mov_b32_e32 v132, v4
	v_mul_f32_e32 v11, v12, v11
	v_mul_f32_e32 v10, v10, v11
	v_cvt_pk_bf16_f32 v9, v9, v10
	global_store_dwordx2 v[22:23], v[8:9], off offset:1600
	v_mov_b32_e32 v8, v114
	v_mov_b32_e32 v9, v115
	v_lshlrev_b32_e32 v10, 16, v8
	v_mul_f32_e32 v11, 0x3d372713, v10
	v_mul_f32_e32 v11, v11, v10
	v_fma_f32 v11, v11, v10, v10
	v_mul_f32_e32 v11, 0x3f4c422a, v11
	v_add_f32_e32 v11, v11, v11
	v_mul_f32_e32 v11, 0x3fb8aa3b, v11
	v_exp_f32_e32 v11, v11
	v_mul_f32_e32 v12, 0.5, v10
	v_add_f32_e32 v11, 1.0, v11
	v_rcp_f32_e32 v11, v11
	s_nop 0
	v_fma_f32 v21, v11, -2.0, 1.0
	v_pk_add_f32 v[10:11], v[20:21], v[132:133]
	v_mov_b32_e32 v132, v5
	v_mul_f32_e32 v4, v12, v11
	v_mul_f32_e32 v10, v10, v4
	v_and_b32_e32 v4, 0xffff0000, v8
	v_mul_f32_e32 v8, 0x3d372713, v4
	v_mul_f32_e32 v8, v8, v4
	v_fma_f32 v8, v8, v4, v4
	v_mul_f32_e32 v8, 0x3f4c422a, v8
	v_add_f32_e32 v8, v8, v8
	v_mul_f32_e32 v8, 0x3fb8aa3b, v8
	v_exp_f32_e32 v8, v8
	s_nop 0
	v_add_f32_e32 v8, 1.0, v8
	v_rcp_f32_e32 v8, v8
	s_nop 0
	v_fma_f32 v21, v8, -2.0, 1.0
	v_mul_f32_e32 v8, 0.5, v4
	v_pk_add_f32 v[4:5], v[20:21], v[132:133]
	v_mov_b32_e32 v132, v6
	v_mul_f32_e32 v5, v8, v5
	v_mul_f32_e32 v4, v4, v5
	v_lshlrev_b32_e32 v5, 16, v9
	v_mul_f32_e32 v8, 0x3d372713, v5
	v_mul_f32_e32 v8, v8, v5
	v_fma_f32 v8, v8, v5, v5
	v_mul_f32_e32 v8, 0x3f4c422a, v8
	v_add_f32_e32 v8, v8, v8
	v_mul_f32_e32 v8, 0x3fb8aa3b, v8
	v_exp_f32_e32 v8, v8
	v_and_b32_e32 v6, 0xffff0000, v9
	v_cvt_pk_bf16_f32 v4, v10, v4
	v_mul_f32_e32 v5, 0.5, v5
	v_add_f32_e32 v8, 1.0, v8
	v_rcp_f32_e32 v8, v8
	s_nop 0
	v_fma_f32 v21, v8, -2.0, 1.0
	v_mul_f32_e32 v8, 0x3d372713, v6
	v_mul_f32_e32 v8, v8, v6
	v_fma_f32 v8, v8, v6, v6
	v_mul_f32_e32 v8, 0x3f4c422a, v8
	v_add_f32_e32 v8, v8, v8
	v_mul_f32_e32 v8, 0x3fb8aa3b, v8
	v_exp_f32_e32 v8, v8
	v_pk_add_f32 v[10:11], v[20:21], v[132:133]
	v_mov_b32_e32 v132, v7
	v_mul_f32_e32 v5, v5, v11
	v_add_f32_e32 v8, 1.0, v8
	v_rcp_f32_e32 v8, v8
	v_mul_f32_e32 v5, v10, v5
	v_fma_f32 v21, v8, -2.0, 1.0
	v_mul_f32_e32 v8, 0.5, v6
	v_pk_add_f32 v[6:7], v[20:21], v[132:133]
	s_nop 0
	v_mul_f32_e32 v7, v8, v7
	v_mul_f32_e32 v6, v6, v7
	v_cvt_pk_bf16_f32 v5, v5, v6
	global_store_dwordx2 v[22:23], v[4:5], off offset:1632
	s_cbranch_scc0 .LBB0_285
.LBB0_290:
	s_waitcnt vmcnt(5)
	v_mov_b32_e32 v4, v212
	v_mov_b32_e32 v5, v213
	v_mov_b32_e32 v6, v214
	v_mov_b32_e32 v7, v215
	v_lshl_add_u64 v[230:231], v[44:45], 0, s[2:3]
	global_load_dwordx2 v[220:221], v[230:231], off offset:-64
	global_load_dword v228, v[46:47], off
	global_load_dwordx2 v[222:223], v[230:231], off offset:-32
	global_load_dwordx2 v[224:225], v[230:231], off
	global_load_dwordx2 v[226:227], v[230:231], off offset:32
	ds_read2_b64 v[8:11], v37 offset1:1
	v_add_u32_e32 v16, 0x3180, v37
	v_add_u32_e32 v12, 0x1080, v37
	v_lshl_add_u64 v[20:21], v[48:49], 0, s[16:17]
	ds_read2_b64 v[58:61], v16 offset1:1
	v_lshl_add_u64 v[22:23], v[48:49], 0, s[18:19]
	ds_read2_b64 v[12:15], v12 offset1:1
	s_andn2_b64 vcc, exec, s[10:11]
	s_waitcnt lgkmcnt(2)
	v_mfma_f32_16x16x32_bf16 v[16:19], v[8:11], v[4:7], 0
	v_add_u32_e32 v8, 0x2100, v37
	ds_read2_b64 v[8:11], v8 offset1:1
	global_load_dwordx4 v[24:27], v[20:21], off offset:-64
	s_nop 0
	global_load_dwordx4 v[20:23], v[22:23], off offset:-64
	s_waitcnt lgkmcnt(1)
	v_mfma_f32_16x16x32_bf16 v[12:15], v[12:15], v[4:7], 0
	s_waitcnt lgkmcnt(0)
	v_mfma_f32_16x16x32_bf16 v[8:11], v[8:11], v[4:7], 0
	v_mfma_f32_16x16x32_bf16 v[4:7], v[58:61], v[4:7], 0
	s_cbranch_vccz .LBB0_293
	s_andn2_b64 vcc, exec, s[6:7]
	s_cbranch_vccz .LBB0_294

.LBB0_293:
	s_waitcnt vmcnt(7)
	v_mov_b32_e32 v58, v216
	v_mov_b32_e32 v59, v217
	v_mov_b32_e32 v60, v218
	v_mov_b32_e32 v61, v219
	ds_read2_b64 v[62:65], v37 offset0:8 offset1:9
	v_add_u32_e32 v57, 0x10c0, v37
	s_waitcnt lgkmcnt(0)
	v_mfma_f32_16x16x32_bf16 v[16:19], v[62:65], v[58:61], v[16:19]
	ds_read2_b64 v[62:65], v57 offset1:1
	v_add_u32_e32 v57, 0x2140, v37
	s_waitcnt lgkmcnt(0)
	v_mfma_f32_16x16x32_bf16 v[12:15], v[62:65], v[58:61], v[12:15]
	ds_read2_b64 v[62:65], v57 offset1:1
	v_add_u32_e32 v57, 0x31c0, v37
	s_waitcnt lgkmcnt(0)
	v_mfma_f32_16x16x32_bf16 v[8:11], v[62:65], v[58:61], v[8:11]
	ds_read2_b64 v[62:65], v57 offset1:1
	s_waitcnt lgkmcnt(0)
	v_mfma_f32_16x16x32_bf16 v[4:7], v[62:65], v[58:61], v[4:7]
	s_andn2_b64 vcc, exec, s[6:7]
	s_cbranch_vccnz .LBB0_292
